# DIFF fast path: next-tile LDS-DMA issued between QK MFMAs using scalar-base + per-lane-offset addressing (no per-tile address VALU), QK(sub0) K fragments 8-deep
# speedup vs baseline: 1.0718x; 1.0209x over previous
; #define MFMA(a, b, c) __builtin_amdgcn_mfma_f32_32x32x16_bf16((a), (b), (c), 0, 0, 0)
; #define GLDS16(g, l) __builtin_amdgcn_global_load_lds((const unsigned*)(g), (unsigned*)(l), 16, 0, 0)
; #define GLDS4(g, l) __builtin_amdgcn_global_load_lds((const unsigned*)(g), (unsigned*)(l), 4, 0, 0)
; DI int tid_pinned() { int t = threadIdx.x; asm volatile("" : "+v"(t)); return t; }
; DI f32x16 zero16() { f32x16 z; for (int r = 0; r < 16; ++r) z[r] = 0.f; return z; }
; template <bool DIFF>
; DI void attn_phase(const AttnArgs& a, char* lds) {
;     ...
;     for (int t = t_beg; t < t_end; ++t) {
;       const char* sb = lds + (t & 1) * STAGE;
;       char* nb = lds + ((t + 1) & 1) * STAGE;
;       const bool nxt = t + 1 < t_end;
;       const int4 tinfo = *(const int4*)(ttab + 4 * t);
;       const int kcmin = __builtin_amdgcn_readfirstlane(tinfo.x), kcmax = __builtin_amdgcn_readfirstlane(tinfo.y);
;       bool skip = kcmin > wqcmax;
;       if (DIFF) {
;         const int tpmin = __builtin_amdgcn_readfirstlane(tinfo.z), tpmax = __builtin_amdgcn_readfirstlane(tinfo.w);
;         const int dist = max(0, max(wpmin - tpmax, tpmin - wpmax));
;         skip = skip || (slope2 * (float)dist > lim2);
;       }
;       const bool needmask = kcmax > wqcmin;
;       if (nxt) {
;         const int t2 = tid_pinned();
;         const u32 kofs = KOFS(t2), vofs = VOFS(t2);
;         const u32 ko2 = kofs + (u32)(t + 1) * 64u * (u32)a.ldk;
; #pragma unroll
;         for (int i = 0; i < NKR; ++i) GLDS16(a.K + ko2 + i * 64, nb + wave * 1024 + 8192 * i);
;         const u32 vo2 = vofs + (u32)(t + 1) * (u32)(DV * 64);
; #pragma unroll
;         for (int i = 0; i < NVR; ++i) GLDS16(a.VT + vo2 + i * 4096, nb + KBYTES + wave * 1024 + 8192 * i);
;         if (wave == 0) { const int l4 = (t + 1) * 64 + (t2 & 63); GLDS4(a.pos + l4, nb + KBYTES + VBYTES); GLDS4(a.posf + l4, nb + KBYTES + VBYTES + 256); }
;       }
;     ...
;         bf16x8 kf[NDS];
; #pragma unroll
;         for (int ds = 0; ds < NDS; ++ds) kf[ds] = *(const bf16x8*)(sb + koffb + (ds >> 2) * 8192 + ((((ds & 3) * 2) ^ kx) << 4));
;         f32x16 s0, s1;
;         s0 = MFMA(kf[0], qf[0], zero16());
; #pragma unroll
;         for (int ds = 1; ds < NDS; ++ds) s0 = MFMA(kf[ds], qf[ds], s0);
.LBB0_599:
	v_mov_b32_e32 v0, s80
	ds_read_b128 v[2:5], v0
	s_add_i32 s83, s1, 1
	s_cmp_ge_i32 s83, s78
	s_cselect_b64 s[66:67], -1, 0
	s_bitcmp1_b32 s83, 0
	s_cselect_b32 s85, 0x10200, 0
	s_add_i32 s86, s85, s33
	s_waitcnt lgkmcnt(0)
	v_readfirstlane_b32 s0, v2
	v_readfirstlane_b32 s4, v3
	v_readfirstlane_b32 s5, v4
	v_readfirstlane_b32 s8, v5
	s_nop 1
	v_subrev_u32_e32 v0, s8, v219
	v_sub_u32_e32 v2, s5, v217
	v_max3_i32 v0, v0, v2, 0
	v_cvt_f32_u32_e32 v0, v0
	s_bitcmp1_b32 s1, 0
	s_cselect_b32 s84, 0x10200, 0
	s_cmp_gt_i32 s0, s77
	v_mul_f32_e32 v0, v223, v0
	s_cselect_b64 s[0:1], -1, 0
	v_cmp_gt_f32_e32 vcc, v0, v218
	v_mov_b32_e32 v0, v222
	s_or_b64 s[68:69], s[0:1], vcc
	s_nop 0
	v_readfirstlane_b32 s0, v0
	s_cmp_eq_u32 s0, 0
	s_cselect_b64 s[8:9], -1, 0
	s_or_b64 s[8:9], s[8:9], s[68:69]
	s_and_b64 vcc, exec, s[8:9]
	v_cmp_gt_i32_e64 s[8:9], s4, v220
	s_nop 1
	v_cndmask_b32_e64 v0, 0, 1, s[8:9]
	v_cmp_ne_u32_e64 s[8:9], 1, v0
	s_cbranch_vccnz .Ldiff_slow
	s_or_b64 vcc, s[66:67], s[6:7]
	s_and_b64 vcc, exec, vcc
	s_cbranch_vccnz .Ldiff_nw0
	v_and_b32_e32 v0, 63, v208
	v_add_u32_e32 v2, s81, v0
	v_ashrrev_i32_e32 v3, 31, v2
	v_lshlrev_b64 v[2:3], 2, v[2:3]
	v_lshl_add_u64 v[4:5], s[48:49], 0, v[2:3]
	s_add_i32 m0, s85, 0x10000
	v_lshl_add_u64 v[2:3], s[38:39], 0, v[2:3]
	global_load_lds_dword v[2:3], off
	s_add_i32 m0, s85, 0x10100
	s_nop 0
	global_load_lds_dword v[4:5], off
.Ldiff_nw0:
	v_mov_b32_e32 v2, v208
	s_add_i32 s1, s35, s84
	v_lshlrev_b32_e32 v3, 1, v2
	v_and_b32_e32 v4, 8, v3
	v_lshrrev_b32_e32 v3, 1, v2
	v_and_b32_e32 v5, 4, v3
	v_and_b32_e32 v6, 19, v2
	v_or3_b32 v4, v4, v6, v5
	v_bfe_u32 v0, v2, 5, 1
	v_lshrrev_b32_e32 v5, 1, v4
	v_bitop3_b32 v5, v5, v0, 7 bitop3:0x6c
	v_lshl_add_u32 v144, v4, 7, s1
	v_lshlrev_b32_e32 v145, 4, v5
	v_add_u32_e32 v146, v144, v145
	v_lshrrev_b32_e32 v209, 4, v208
	v_xor_b32_e32 v209, v209, v208
	v_lshlrev_b32_e32 v209, 3, v209
	v_and_b32_e32 v209, 56, v209
	v_ashrrev_i32_e32 v253, 3, v208
	v_lshlrev_b32_e32 v209, 1, v209
	v_lshl_add_u32 v255, v253, 7, v209
	v_lshl_add_u32 v209, v253, 13, v209
	s_lshl_b32 s87, s81, 12
	s_add_i32 s87, s87, s79
	s_lshl_b32 s87, s87, 1
	s_add_u32 s98, s30, s87
	s_addc_u32 s99, s31, 0
	s_lshl_b32 s87, s82, 1
	s_add_u32 s52, s36, s87
	s_addc_u32 s53, s37, 0
	s_and_b64 vcc, exec, s[66:67]
	v_xad_u32 v147, v145, 32, v144
	v_xad_u32 v148, v145, 64, v144
	v_xad_u32 v144, v145, s74, v144
	ds_read_b128 v[8:11], v146
	ds_read_b128 v[12:15], v147
	ds_read_b128 v[228:231], v148
	ds_read_b128 v[232:235], v144
	ds_read_b128 v[236:239], v146 offset:8192
	ds_read_b128 v[240:243], v147 offset:8192
	ds_read_b128 v[244:247], v148 offset:8192
	ds_read_b128 v[4:7], v144 offset:8192
	ds_read_b128 v[248:251], v144 offset:12288
	v_lshlrev_b32_e32 v252, 5, v0
	v_add_u32_e32 v227, s84, v252
	s_add_i32 s1, s84, 0x10000
	s_waitcnt lgkmcnt(8)
	v_mfma_f32_32x32x16_bf16 v[160:175], v[8:11], v[176:179], 0
	ds_read_b128 v[8:11], v146 offset:4096
	s_cbranch_vccnz .Ldiff_nd0
	s_mov_b32 m0, s86
	s_nop 0
	global_load_lds_dwordx4 v209, s[98:99]
.Ldiff_nd0:
	s_waitcnt lgkmcnt(8)
	v_mfma_f32_32x32x16_bf16 v[160:175], v[12:15], v[180:183], v[160:175]
	ds_read_b128 v[12:15], v147 offset:4096
	s_cbranch_vccnz .Ldiff_nd1
	s_add_i32 m0, s86, 0x2000
	s_add_u32 s88, s98, s42
	s_addc_u32 s89, s99, s43
	global_load_lds_dwordx4 v209, s[88:89]
.Ldiff_nd1:
	s_waitcnt lgkmcnt(8)
	v_mfma_f32_32x32x16_bf16 v[160:175], v[228:231], v[184:187], v[160:175]
	ds_read_b128 v[228:231], v148 offset:4096
	s_cbranch_vccnz .Ldiff_nd2
	s_add_i32 m0, s86, 0x4000
	s_add_u32 s88, s98, s56
	s_addc_u32 s89, s99, s57
	global_load_lds_dwordx4 v209, s[88:89]
.Ldiff_nd2:
	s_waitcnt lgkmcnt(8)
	v_mfma_f32_32x32x16_bf16 v[160:175], v[232:235], v[188:191], v[160:175]
	ds_read_b128 v[232:235], v144 offset:4096
	s_cbranch_vccnz .Ldiff_nd3
	s_add_i32 m0, s86, 0x6000
	s_add_u32 s88, s98, s58
	s_addc_u32 s89, s99, s59
	global_load_lds_dwordx4 v209, s[88:89]
.Ldiff_nd3:
	v_mov_b32_e32 v209, 0x6000
	s_waitcnt lgkmcnt(8)
	v_mfma_f32_32x32x16_bf16 v[160:175], v[236:239], v[192:195], v[160:175]
	ds_read_b128 v[236:239], v146 offset:12288
	s_cbranch_vccnz .Ldiff_nd4
	s_add_i32 m0, s86, 0x8000
	s_nop 0
	global_load_lds_dwordx4 v255, s[52:53]
.Ldiff_nd4:
	s_waitcnt lgkmcnt(8)
	v_mfma_f32_32x32x16_bf16 v[160:175], v[240:243], v[196:199], v[160:175]
	ds_read_b128 v[240:243], v147 offset:12288
	s_cbranch_vccnz .Ldiff_nd5
	s_add_i32 m0, s86, 0xa000
	s_add_u32 s88, s52, s60
	s_addc_u32 s89, s53, s61
	global_load_lds_dwordx4 v255, s[88:89]
; #define MFMA(a, b, c) __builtin_amdgcn_mfma_f32_32x32x16_bf16((a), (b), (c), 0, 0, 0)
; DI f32x16 zero16() { f32x16 z; for (int r = 0; r < 16; ++r) z[r] = 0.f; return z; }
; #define DIFF_MASK(sv, sub_) do { if (needmask) { _Pragma("unroll") for (int r = 0; r < 16; ++r) { const int kl_ = (sub_) * 32 + ((r < 8) ? (8 * g2 + r) : (16 + 8 * g2 + (r - 8))); \
;           if ((pki[kl_] >> 6) > (((int)qposf) >> 6)) sv[r] = -__builtin_inff(); } } } while (0)
; template <bool DIFF>
; DI void attn_phase(const AttnArgs& a, char* lds) {
;     ...
;         for (int ds = 1; ds < NDS; ++ds) s0 = MFMA(kf[ds], qf[ds], s0);
; #pragma unroll
;         for (int ds = 0; ds < NDS; ++ds) kf[ds] = *(const bf16x8*)(sb + koffb + 4096 + (ds >> 2) * 8192 + ((((ds & 3) * 2) ^ kx) << 4));
;         __builtin_amdgcn_sched_barrier(0);
;         {
;           s1 = MFMA(kf[0], qf[0], zero16());
; #pragma unroll
;           for (int ds = 1; ds < NDS; ++ds) s1 = MFMA(kf[ds], qf[ds], s1);
;           DIFF_ALIBI(s0, 0);
;           DIFF_MASK(s0, 0);
.Ldiff_nd5:
	s_waitcnt lgkmcnt(8)
	v_mfma_f32_32x32x16_bf16 v[160:175], v[244:247], v[200:203], v[160:175]
	ds_read_b128 v[244:247], v148 offset:12288
	s_cbranch_vccnz .Ldiff_nd6
	s_add_i32 m0, s86, 0xc000
	s_add_u32 s88, s52, s62
	s_addc_u32 s89, s53, s63
	global_load_lds_dwordx4 v255, s[88:89]
.Ldiff_nd6:
	s_waitcnt lgkmcnt(8)
	v_mfma_f32_32x32x16_bf16 v[160:175], v[4:7], v[204:207], v[160:175]
	s_cbranch_vccnz .Ldiff_nd7
	s_add_i32 m0, s86, 0xe000
	s_add_u32 s88, s52, s64
	s_addc_u32 s89, s53, s65
	global_load_lds_dwordx4 v255, s[88:89]
.Ldiff_nd7:
	s_waitcnt lgkmcnt(6)
	v_mfma_f32_32x32x16_bf16 v[144:159], v[8:11], v[176:179], 0
	v_add_u32_e32 v253, 0x10100, v227
	ds_read_b128 v[4:7], v253
	ds_read_b128 v[8:11], v253 offset:16
	s_and_b64 vcc, exec, s[8:9]
	s_waitcnt lgkmcnt(1)
	v_sub_f32_e32 v4, v221, v4
	v_sub_f32_e32 v5, v221, v5
	v_mfma_f32_32x32x16_bf16 v[144:159], v[12:15], v[180:183], v[144:159]
	v_sub_f32_e32 v6, v221, v6
	v_sub_f32_e32 v7, v221, v7
	s_waitcnt lgkmcnt(0)
	v_sub_f32_e32 v12, v221, v8
	v_sub_f32_e32 v13, v221, v9
	v_sub_f32_e32 v14, v221, v10
	v_sub_f32_e32 v15, v221, v11
	v_mfma_f32_32x32x16_bf16 v[144:159], v[228:231], v[184:187], v[144:159]
	v_fma_f32 v11, -v223, |v4|, v160
	v_fma_f32 v9, -v223, |v5|, v161
	v_fma_f32 v10, -v223, |v6|, v162
	v_fma_f32 v8, -v223, |v7|, v163
	v_fma_f32 v7, -v223, |v12|, v164
	v_fma_f32 v6, -v223, |v13|, v165
	v_fma_f32 v5, -v223, |v14|, v166
	v_mfma_f32_32x32x16_bf16 v[144:159], v[232:235], v[188:191], v[144:159]
	v_fma_f32 v4, -v223, |v15|, v167
	ds_read_b128 v[12:15], v253 offset:64
	ds_read_b128 v[160:163], v253 offset:80
	s_waitcnt lgkmcnt(1)
	v_sub_f32_e32 v12, v221, v12
	v_mfma_f32_32x32x16_bf16 v[144:159], v[236:239], v[192:195], v[144:159]
	v_sub_f32_e32 v13, v221, v13
	v_sub_f32_e32 v14, v221, v14
	v_sub_f32_e32 v15, v221, v15
	s_waitcnt lgkmcnt(0)
	v_sub_f32_e32 v165, v221, v160
	v_sub_f32_e32 v166, v221, v161
	v_sub_f32_e32 v167, v221, v162
	v_sub_f32_e32 v163, v221, v163
	v_mfma_f32_32x32x16_bf16 v[144:159], v[240:243], v[196:199], v[144:159]
	s_nop 0
	v_fma_f32 v164, -v223, |v12|, v168
	v_fma_f32 v162, -v223, |v13|, v169
	v_fma_f32 v160, -v223, |v14|, v170
	v_fma_f32 v161, -v223, |v15|, v171
	v_fma_f32 v15, -v223, |v165|, v172
	v_mfma_f32_32x32x16_bf16 v[144:159], v[244:247], v[200:203], v[144:159]
	v_fma_f32 v14, -v223, |v166|, v173
	v_fma_f32 v13, -v223, |v167|, v174
	v_fma_f32 v12, -v223, |v163|, v175
	v_add_u32_e32 v163, s1, v252
	v_mfma_f32_32x32x16_bf16 v[144:159], v[248:251], v[204:207], v[144:159]
	s_cbranch_vccnz .LBB0_605
	ds_read_b128 v[166:169], v163
	v_add_u32_e32 v165, 0x10050, v227
	ds_read_b128 v[170:173], v165
	s_waitcnt lgkmcnt(1)
	v_ashrrev_i32_e32 v165, 6, v166
	v_ashrrev_i32_e32 v166, 6, v167
	v_cmp_le_i32_e32 vcc, v165, v224
	v_ashrrev_i32_e32 v165, 6, v168
	s_nop 0
	v_cndmask_b32_e32 v11, v216, v11, vcc
	v_cmp_le_i32_e32 vcc, v166, v224
	v_add_u32_e32 v166, 0x10010, v227
	s_nop 0
	v_cndmask_b32_e32 v9, v216, v9, vcc
	v_cmp_le_i32_e32 vcc, v165, v224
	v_ashrrev_i32_e32 v165, 6, v169
	ds_read_b128 v[166:169], v166
	v_cndmask_b32_e32 v10, v216, v10, vcc
	v_cmp_le_i32_e32 vcc, v165, v224
	v_add_u32_e32 v165, 0x10040, v227
	ds_read_b128 v[228:231], v165
	s_waitcnt lgkmcnt(1)
	v_ashrrev_i32_e32 v165, 6, v166
	v_cndmask_b32_e32 v8, v216, v8, vcc
	v_cmp_le_i32_e32 vcc, v165, v224
	v_ashrrev_i32_e32 v165, 6, v167
	s_nop 0
	v_cndmask_b32_e32 v7, v216, v7, vcc
	v_cmp_le_i32_e32 vcc, v165, v224
	v_ashrrev_i32_e32 v165, 6, v168
	s_nop 0
	v_cndmask_b32_e32 v6, v216, v6, vcc
	v_cmp_le_i32_e32 vcc, v165, v224
	v_ashrrev_i32_e32 v165, 6, v169
	s_nop 0
	v_cndmask_b32_e32 v5, v216, v5, vcc
	v_cmp_le_i32_e32 vcc, v165, v224
	s_waitcnt lgkmcnt(0)
	v_ashrrev_i32_e32 v165, 6, v228
	v_cndmask_b32_e32 v4, v216, v4, vcc
	v_cmp_le_i32_e32 vcc, v165, v224
	v_ashrrev_i32_e32 v165, 6, v229
	s_nop 0
	v_cndmask_b32_e32 v164, v216, v164, vcc
	v_cmp_le_i32_e32 vcc, v165, v224
	v_ashrrev_i32_e32 v165, 6, v230
	s_nop 0
	v_cndmask_b32_e32 v162, v216, v162, vcc
	v_cmp_le_i32_e32 vcc, v165, v224
	v_ashrrev_i32_e32 v165, 6, v231
	s_nop 0
	v_cndmask_b32_e32 v160, v216, v160, vcc
	v_cmp_le_i32_e32 vcc, v165, v224
	v_ashrrev_i32_e32 v165, 6, v170
	s_nop 0
	v_cndmask_b32_e32 v161, v216, v161, vcc
	v_cmp_le_i32_e32 vcc, v165, v224
	v_ashrrev_i32_e32 v165, 6, v171
	s_nop 0
	v_cndmask_b32_e32 v15, v216, v15, vcc
	v_cmp_le_i32_e32 vcc, v165, v224
	v_ashrrev_i32_e32 v165, 6, v172
	s_nop 0
	v_cndmask_b32_e32 v14, v216, v14, vcc
	v_cmp_le_i32_e32 vcc, v165, v224
	v_ashrrev_i32_e32 v165, 6, v173
	s_nop 0
	v_cndmask_b32_e32 v13, v216, v13, vcc
	v_cmp_le_i32_e32 vcc, v165, v224
	s_nop 1
	v_cndmask_b32_e32 v12, v216, v12, vcc

; #define GLDS16(g, l) __builtin_amdgcn_global_load_lds((const unsigned*)(g), (unsigned*)(l), 16, 0, 0)
; #define GLDS4(g, l) __builtin_amdgcn_global_load_lds((const unsigned*)(g), (unsigned*)(l), 4, 0, 0)
; DI int tid_pinned() { int t = threadIdx.x; asm volatile("" : "+v"(t)); return t; }
; template <bool DIFF>
; DI void attn_phase(const AttnArgs& a, char* lds) {
;     ...
;       if (nxt) {
;         const int t2 = tid_pinned();
;         const u32 kofs = KOFS(t2), vofs = VOFS(t2);
;         const u32 ko2 = kofs + (u32)(t + 1) * 64u * (u32)a.ldk;
; #pragma unroll
;         for (int i = 0; i < NKR; ++i) GLDS16(a.K + ko2 + i * 64, nb + wave * 1024 + 8192 * i);
;         const u32 vo2 = vofs + (u32)(t + 1) * (u32)(DV * 64);
; #pragma unroll
;         for (int i = 0; i < NVR; ++i) GLDS16(a.VT + vo2 + i * 4096, nb + KBYTES + wave * 1024 + 8192 * i);
;         if (wave == 0) { const int l4 = (t + 1) * 64 + (t2 & 63); GLDS4(a.pos + l4, nb + KBYTES + VBYTES); GLDS4(a.posf + l4, nb + KBYTES + VBYTES + 256); }
;       }
.Ldiff_slow:
	s_and_b64 vcc, exec, s[66:67]
	s_cbranch_vccnz .LBB0_608
	v_mov_b32_e32 v2, v208
	v_lshrrev_b32_e32 v0, 4, v2
	v_xor_b32_e32 v0, v0, v2
	v_ashrrev_i32_e32 v3, 3, v2
	v_lshlrev_b32_e32 v0, 3, v0
	v_and_b32_e32 v8, 56, v0
	v_add_u32_e32 v0, s81, v3
	v_lshl_add_u32 v0, v0, 12, s79
	v_or_b32_e32 v0, v0, v8
	v_lshl_add_u64 v[4:5], v[0:1], 1, s[30:31]
	s_mov_b32 m0, s86
	v_lshl_add_u64 v[6:7], v[4:5], 0, s[42:43]
	global_load_lds_dwordx4 v[4:5], off
	s_add_i32 m0, s86, 0x2000
	v_lshl_or_b32 v0, v3, 6, v8
	global_load_lds_dwordx4 v[6:7], off
	v_lshl_add_u64 v[6:7], v[4:5], 0, s[56:57]
	s_add_i32 m0, s86, 0x4000
	v_lshl_add_u64 v[4:5], v[4:5], 0, s[58:59]
	global_load_lds_dwordx4 v[6:7], off
	s_add_i32 m0, s86, 0x6000
	v_add_u32_e32 v0, s82, v0
	global_load_lds_dwordx4 v[4:5], off
	s_add_i32 m0, s86, 0x8000
	v_lshl_add_u64 v[4:5], v[0:1], 1, s[36:37]
	global_load_lds_dwordx4 v[4:5], off
	v_lshl_add_u64 v[6:7], v[4:5], 0, s[60:61]
	s_add_i32 m0, s86, 0xa000
	s_and_b64 vcc, exec, s[6:7]
	global_load_lds_dwordx4 v[6:7], off
	v_lshl_add_u64 v[6:7], v[4:5], 0, s[62:63]
	s_add_i32 m0, s86, 0xc000
	v_lshl_add_u64 v[4:5], v[4:5], 0, s[64:65]
	global_load_lds_dwordx4 v[6:7], off
	s_add_i32 m0, s86, 0xe000
	s_nop 0
	global_load_lds_dwordx4 v[4:5], off
	s_cbranch_vccnz .LBB0_608
	v_and_b32_e32 v0, 63, v2
	v_add_u32_e32 v2, s81, v0
	v_ashrrev_i32_e32 v3, 31, v2
	v_lshlrev_b64 v[2:3], 2, v[2:3]
	v_lshl_add_u64 v[4:5], s[48:49], 0, v[2:3]
	s_add_i32 m0, s85, 0x10000
	v_lshl_add_u64 v[2:3], s[38:39], 0, v[2:3]
	global_load_lds_dword v[2:3], off
	s_add_i32 m0, s85, 0x10100
	s_nop 0
	global_load_lds_dword v[4:5], off
	s_branch .LBB0_608

; __global__ void __launch_bounds__(512) mega_fwd(Params p) {
;   __shared__ __attribute__((aligned(16))) char lds[LDS_BYTES];
	.amdhsa_kernel _Z8mega_fwd6Params
		.amdhsa_group_segment_fixed_size 139264
		.amdhsa_private_segment_fixed_size 0
		.amdhsa_kernarg_size 440
		.amdhsa_user_sgpr_count 2
		.amdhsa_user_sgpr_dispatch_ptr 0
		.amdhsa_user_sgpr_queue_ptr 0
		.amdhsa_user_sgpr_kernarg_segment_ptr 1
		.amdhsa_user_sgpr_dispatch_id 0
		.amdhsa_user_sgpr_kernarg_preload_length 0
		.amdhsa_user_sgpr_kernarg_preload_offset 0
		.amdhsa_user_sgpr_private_segment_size 0
		.amdhsa_uses_dynamic_stack 0
		.amdhsa_enable_private_segment 0
		.amdhsa_system_sgpr_workgroup_id_x 1
		.amdhsa_system_sgpr_workgroup_id_y 0
		.amdhsa_system_sgpr_workgroup_id_z 0
		.amdhsa_system_sgpr_workgroup_info 0
		.amdhsa_system_vgpr_workitem_id 2
		.amdhsa_next_free_vgpr 256
		.amdhsa_next_free_sgpr 100
		.amdhsa_accum_offset 256
		.amdhsa_reserve_vcc 1
		.amdhsa_float_round_mode_32 0
		.amdhsa_float_round_mode_16_64 0
		.amdhsa_float_denorm_mode_32 3
		.amdhsa_float_denorm_mode_16_64 3
		.amdhsa_dx10_clamp 1
		.amdhsa_ieee_mode 1
		.amdhsa_fp16_overflow 0
		.amdhsa_tg_split 0
		.amdhsa_exception_fp_ieee_invalid_op 0
		.amdhsa_exception_fp_denorm_src 0
		.amdhsa_exception_fp_ieee_div_zero 0
		.amdhsa_exception_fp_ieee_overflow 0
		.amdhsa_exception_fp_ieee_underflow 0
		.amdhsa_exception_fp_ieee_inexact 0
		.amdhsa_exception_int_div_zero 0
	.end_amdhsa_kernel

; __global__ void __launch_bounds__(512) mega_fwd(Params p) {
;   __shared__ __attribute__((aligned(16))) char lds[LDS_BYTES];
amdhsa.kernels:
  - .agpr_count:     0
    .args:
      - .offset:         0
        .size:           184
        .value_kind:     by_value
      - .offset:         184
        .size:           4
        .value_kind:     hidden_block_count_x
      - .offset:         188
        .size:           4
        .value_kind:     hidden_block_count_y
      - .offset:         192
        .size:           4
        .value_kind:     hidden_block_count_z
      - .offset:         196
        .size:           2
        .value_kind:     hidden_group_size_x
      - .offset:         198
        .size:           2
        .value_kind:     hidden_group_size_y
      - .offset:         200
        .size:           2
        .value_kind:     hidden_group_size_z
      - .offset:         202
        .size:           2
        .value_kind:     hidden_remainder_x
      - .offset:         204
        .size:           2
        .value_kind:     hidden_remainder_y
      - .offset:         206
        .size:           2
        .value_kind:     hidden_remainder_z
      - .offset:         224
        .size:           8
        .value_kind:     hidden_global_offset_x
      - .offset:         232
        .size:           8
        .value_kind:     hidden_global_offset_y
      - .offset:         240
        .size:           8
        .value_kind:     hidden_global_offset_z
      - .offset:         248
        .size:           2
        .value_kind:     hidden_grid_dims
      - .offset:         272
        .size:           8
        .value_kind:     hidden_multigrid_sync_arg
    .group_segment_fixed_size: 139264
    .kernarg_segment_align: 8
    .kernarg_segment_size: 440
    .language:       OpenCL C
    .language_version:
      - 2
      - 0
    .max_flat_workgroup_size: 512
    .name:           _Z8mega_fwd6Params
    .private_segment_fixed_size: 0
    .sgpr_count:     106
    .sgpr_spill_count: 16
    .symbol:         _Z8mega_fwd6Params.kd
    .uniform_work_group_size: 1
    .uses_dynamic_stack: false
    .vgpr_count:     256
    .vgpr_spill_count: 0
    .wavefront_size: 64
